# MFMA-based accumulator zeroing also in the sequence-DFT, channel-DFT and down-projection phases
# baseline (speedup 1.0000x reference)
.LBB0_179:
	s_cmp_lt_i32 s33, 1
	s_cbranch_scc1 .LBB0_187
	s_add_i32 s7, s33, -4
	s_add_u32 vcc_lo, s42, 0x180
	s_addc_u32 vcc_hi, s43, 0
	s_add_u32 s42, s46, 0x180
	v_mov_b32_e32 v76, 0
	v_mov_b32_e32 v77, 0
	v_mov_b32_e32 v78, 0
	v_mov_b32_e32 v79, 0
	s_addc_u32 s43, s47, 0
	s_mov_b32 s52, 0
	s_nop 1
	v_mfma_f32_32x32x16_bf16 v[0:15], v[76:79], v[76:79], 0
	v_mfma_f32_32x32x16_bf16 v[16:31], v[76:79], v[76:79], 0
	v_mfma_f32_32x32x16_bf16 v[32:47], v[76:79], v[76:79], 0
	v_mfma_f32_32x32x16_bf16 v[48:63], v[76:79], v[76:79], 0

.LBB0_237:
	s_mov_b32 s9, 4
	s_cmp_lt_i32 s9, 1
	s_cbranch_scc1 .LBB0_249
	s_add_i32 s19, s9, -2
	s_add_u32 s33, s42, 0x100
	s_addc_u32 s76, s43, 0
	s_add_u32 s38, s38, 0x10080
	v_mov_b32_e32 v140, 0
	v_mov_b32_e32 v141, 0
	v_mov_b32_e32 v142, 0
	v_mov_b32_e32 v143, 0
	s_addc_u32 s39, s39, 0
	s_mov_b32 s42, 0
	s_nop 1
	v_mfma_f32_32x32x16_bf16 v[0:15], v[140:143], v[140:143], 0
	v_mfma_f32_32x32x16_bf16 v[16:31], v[140:143], v[140:143], 0
	v_mfma_f32_32x32x16_bf16 v[32:47], v[140:143], v[140:143], 0
	v_mfma_f32_32x32x16_bf16 v[48:63], v[140:143], v[140:143], 0
	v_mfma_f32_32x32x16_bf16 v[64:79], v[140:143], v[140:143], 0
	v_mfma_f32_32x32x16_bf16 v[80:95], v[140:143], v[140:143], 0
	v_mfma_f32_32x32x16_bf16 v[96:111], v[140:143], v[140:143], 0
	v_mfma_f32_32x32x16_bf16 v[112:127], v[140:143], v[140:143], 0

.LBB0_282:
	s_mov_b32 vcc_lo, 44
	s_cmp_lt_i32 vcc_lo, 1
	s_cbranch_scc1 .LBB0_290
	s_add_i32 vcc_hi, vcc_lo, -2
	s_add_u32 s52, s34, 0x100
	v_mov_b32_e32 v70, 0
	v_mov_b32_e32 v71, 0
	v_mov_b32_e32 v72, 0
	v_mov_b32_e32 v73, 0
	s_addc_u32 s53, s35, 0
	s_mov_b32 s38, 0
	s_nop 1
	v_mfma_f32_32x32x16_bf16 v[0:15], v[70:73], v[70:73], 0
	v_mfma_f32_32x32x16_bf16 v[16:31], v[70:73], v[70:73], 0
	v_mfma_f32_32x32x16_bf16 v[32:47], v[70:73], v[70:73], 0
	v_mfma_f32_32x32x16_bf16 v[48:63], v[70:73], v[70:73], 0
